# speedup vs baseline: 1.0097x; 1.0043x over previous
; __global__ void __launch_bounds__(512, 2) fwd_megakernel(Params kp_) {
;     ...
;                             bf16x8 fa1[4], fb1[2], fk1[2]; float uv1[4]; float eg1;
;                             bf16x8 fa2[4], fb2[2], fk2[2]; float uv2[4]; float eg2;
;                             GS_LOAD(fa, fb, fk, uv, eg, 0); GS_LOAD(fa1, fb1, fk1, uv1, eg1, 1);
.LBB0_849:
	s_or_b64 exec, exec, s[2:3]
	s_lshl_b32 s3, s15, 1
	s_bfe_u32 s2, s15, 0x30001
	s_and_b32 s12, s3, 0xe0
	s_and_b32 s100, s12, 0x20
	s_lshl_b32 s100, s100, 6
	s_and_b32 s12, s12, 0xc0
	s_or_b32 s12, s12, s100
	s_lshl_b32 s3, s16, 1
	s_lshl_b32 s8, s2, 1
	s_lshl_b32 s10, s2, 12
	s_and_b32 s2, s3, 14
	s_ashr_i32 s11, s16, 6
	s_add_i32 s2, s2, s11
	s_and_b32 s17, s3, 0x70
	s_ashr_i32 s3, s2, 31
	s_lshl_b64 s[18:19], s[2:3], 20
	s_lshl_b64 s[6:7], s[2:3], 21
	v_readlane_b32 s13, v253, 18
	v_lshl_add_u64 v[0:1], v[130:131], 0, s[6:7]
	v_lshl_add_u64 v[2:3], v[136:137], 0, s[6:7]
	s_add_u32 s6, s13, s6
	v_readlane_b32 s22, v253, 19
	s_addc_u32 s7, s22, s7
	s_lshl_b32 s9, s17, 1
	s_and_b32 s100, s17, 0x10
	s_lshl_b32 s100, s100, 7
	s_and_b32 s101, s17, 0x60
	s_lshl_b32 s101, s101, 1
	s_or_b32 s101, s101, s100
	s_add_u32 s6, s6, s101
	s_waitcnt lgkmcnt(0)
	s_barrier
	global_load_dwordx4 v[60:63], v[0:1], off
	global_load_dwordx4 v[48:51], v[0:1], off offset:64
	global_load_dwordx4 v[52:55], v[0:1], off offset:128
	global_load_dwordx4 v[56:59], v[0:1], off offset:192
	v_lshl_add_u64 v[0:1], v[132:133], 0, s[18:19]
	s_addc_u32 s7, s7, 0
	v_and_b32_e32 v196, 7, v204
	v_lshlrev_b32_e32 v196, 1, v196
	v_and_b32_e32 v145, 8, v204
	v_lshl_or_b32 v196, v145, 7, v196
	global_load_dwordx4 v[40:43], v[0:1], off
	global_load_dwordx4 v[8:11], v[2:3], off
	global_load_dwordx4 v[44:47], v[0:1], off offset:1024
	global_load_dwordx4 v[12:15], v[2:3], off offset:1024
	v_lshl_add_u64 v[0:1], s[6:7], 0, v[196:197]
	v_mov_b32_e32 v145, v197
	v_lshl_add_u64 v[0:1], v[0:1], 0, v[144:145]
	global_load_ushort v2, v[0:1], off
	global_load_ushort v3, v[0:1], off offset:16
	s_lshl_b64 s[6:7], s[2:3], 9
	v_readlane_b32 s3, v253, 10
	s_add_u32 s6, s3, s6
	v_readlane_b32 s3, v253, 11
	s_addc_u32 s7, s3, s7
	s_bitset1_b32 s18, 13
	s_lshl_b64 s[20:21], s[18:19], 1
	s_add_u32 s3, s13, s20
	s_addc_u32 s13, s22, s21
	v_lshl_add_u64 v[4:5], v[132:133], 0, s[18:19]
	s_add_u32 s18, s3, s101
	s_addc_u32 s19, s13, 0
	v_lshl_add_u64 v[6:7], v[136:137], 0, s[20:21]
	s_waitcnt vmcnt(14)
	v_lshl_add_u64 v[64:65], s[18:19], 0, v[196:197]
	v_lshl_add_u64 v[66:67], v[64:65], 0, v[144:145]
	s_lshl_b32 s3, s2, 7
	s_and_b32 s18, s3, 0x180
	s_lshl_b32 s3, s18, 1
	v_lshlrev_b32_e32 v196, 1, v205
	v_mov_b32_e32 v80, 0
	v_mov_b32_e32 v81, v80
	v_mov_b32_e32 v82, v80
	v_mov_b32_e32 v83, v80
	s_waitcnt vmcnt(1)
	v_lshlrev_b32_e32 v68, 16, v2
	global_load_ushort v2, v[0:1], off offset:32
	s_nop 0
	global_load_ushort v0, v[0:1], off offset:48
	s_waitcnt vmcnt(2)
	v_lshlrev_b32_e32 v69, 16, v3
	s_waitcnt vmcnt(1)
	v_lshlrev_b32_e32 v70, 16, v2
	s_waitcnt vmcnt(0)
	v_lshlrev_b32_e32 v71, 16, v0
	v_lshl_add_u64 v[0:1], v[130:131], 0, s[20:21]
	global_load_dwordx4 v[24:27], v[0:1], off
	global_load_dwordx4 v[28:31], v[0:1], off offset:64
	global_load_dwordx4 v[32:35], v[0:1], off offset:128
	global_load_dwordx4 v[36:39], v[0:1], off offset:192
	global_load_dwordx4 v[20:23], v[4:5], off
	s_nop 0
	global_load_dwordx4 v[0:3], v[6:7], off
	global_load_dwordx4 v[16:19], v[4:5], off offset:1024
	s_nop 0
	global_load_dwordx4 v[4:7], v[6:7], off offset:1024
	s_nop 0
	global_load_ushort v64, v[66:67], off
	global_load_ushort v65, v[66:67], off offset:16
	global_load_ushort v72, v[66:67], off offset:32
	s_nop 0
	global_load_ushort v66, v[66:67], off offset:48
	s_waitcnt vmcnt(3)
	v_lshlrev_b32_e32 v64, 16, v64
	global_load_dwordx2 v[146:147], v197, s[6:7]
	v_readlane_b32 s6, v253, 53
	v_readlane_b32 s7, v253, 54
	s_add_u32 s3, s6, s3
	s_addc_u32 s7, s7, 0
	s_add_u32 s6, s3, s9
	s_addc_u32 s7, s7, 0
	v_lshl_add_u64 v[148:149], s[6:7], 0, v[196:197]
	s_add_i32 s6, s11, s8
	s_ashr_i32 s7, s6, 31
	s_lshl_b32 s3, s11, 11
	s_lshl_b64 s[20:21], s[6:7], 21
	s_add_i32 s10, s10, s3
	s_lshl_b64 s[8:9], s[6:7], 9
	s_or_b32 s12, s20, s12
	s_mov_b32 s13, s21
	s_lshl_b64 s[6:7], s[6:7], 20
	s_and_b32 s3, s10, 0xffffe000
	s_waitcnt vmcnt(3)
	v_lshlrev_b32_e32 v65, 16, v65
	s_waitcnt vmcnt(1)
	v_lshlrev_b32_e32 v67, 16, v66
	v_lshlrev_b32_e32 v66, 16, v72
	v_lshl_add_u64 v[150:151], s[12:13], 0, v[138:139]
	v_lshl_add_u64 v[152:153], v[134:135], 0, s[20:21]
	v_mov_b32_e32 v155, s7
	v_or_b32_e32 v154, s6, v140
	v_lshl_add_u64 v[156:157], v[142:143], 0, s[20:21]
	v_or_b32_e32 v158, s3, v173
	s_mov_b32 s3, -3
	s_not_b64 s[100:101], s[0:1]
.LBB0_850:
	v_lshl_add_u64 v[168:169], s[86:87], 0, v[156:157]
	s_mov_b32 s6, 0x8000
	v_add_co_u32_e32 v72, vcc, s6, v168
	v_lshl_add_u64 v[166:167], s[86:87], 0, v[154:155]
	s_nop 0
	v_addc_co_u32_e32 v73, vcc, 0, v169, vcc
	s_mov_b32 s6, 0x4804000
	global_load_dwordx4 v[92:95], v[72:73], off
	global_load_dwordx4 v[96:99], v[72:73], off offset:64
	global_load_dwordx4 v[100:103], v[72:73], off offset:128
	global_load_dwordx4 v[104:107], v[72:73], off offset:192
	v_add_co_u32_e32 v72, vcc, s6, v166
	v_lshl_add_u64 v[162:163], s[86:87], 0, v[152:153]
	s_nop 0
	v_addc_co_u32_e32 v73, vcc, 0, v167, vcc
	s_mov_b32 s6, 0x2808000
	v_add_co_u32_e32 v74, vcc, s6, v162
	v_lshl_add_u64 v[164:165], s[86:87], 0, v[150:151]
	s_nop 0
	v_addc_co_u32_e32 v75, vcc, 0, v163, vcc
	s_mov_b32 s6, 0x18808000
	v_add_co_u32_e32 v108, vcc, s6, v164
	s_add_u32 s10, s86, s8
	s_nop 0
	v_addc_co_u32_e32 v109, vcc, 0, v165, vcc
	s_mov_b64 exec, s[0:1]
	global_load_dwordx4 v[88:91], v[72:73], off
	s_mov_b64 exec, -1
	s_mov_b64 exec, s[0:1]
	global_load_dwordx4 v[84:87], v[72:73], off offset:1024
	s_mov_b64 exec, -1
	global_load_dwordx4 v[76:79], v[74:75], off
	s_nop 0
	global_load_dwordx4 v[72:75], v[74:75], off offset:1024
	s_addc_u32 s11, s87, s9
	s_mov_b64 exec, s[100:101]
	global_load_ushort v145, v[108:109], off
	global_load_ushort v182, v[108:109], off offset:16
	global_load_ushort v183, v[108:109], off offset:32
	global_load_ushort v184, v[108:109], off offset:48
	s_mov_b64 exec, -1
	global_load_dword v160, v239, s[10:11] offset:8
	ds_read_b128 v[108:111], v129
	ds_read_b128 v[112:115], v129 offset:64
	ds_read_b128 v[116:119], v129 offset:128
	ds_read_b128 v[120:123], v129 offset:192
	v_cndmask_b32_e64 v124, 0, 1, s[0:1]
	v_cmp_ne_u32_e64 s[6:7], 1, v124
	s_andn2_b64 vcc, exec, s[0:1]
	s_mov_b64 s[12:13], -1
	s_cbranch_vccnz .LBB0_852
	s_waitcnt lgkmcnt(3)
	v_mfma_f32_16x16x32_bf16 v[124:127], v[108:111], v[60:63], 0
	s_mov_b64 s[12:13], 0
	s_waitcnt lgkmcnt(2)
	v_mfma_f32_16x16x32_bf16 v[124:127], v[112:115], v[48:51], v[124:127]
	s_waitcnt lgkmcnt(1)
	v_mfma_f32_16x16x32_bf16 v[124:127], v[116:119], v[52:55], v[124:127]
	s_waitcnt lgkmcnt(0)
	v_mfma_f32_16x16x32_bf16 v[124:127], v[120:123], v[56:59], v[124:127]

.LBB0_856:
	s_waitcnt vmcnt(13)
	v_pk_mul_f32 v[42:43], v[82:83], v[146:147] op_sel_hi:[1,0]
	v_pk_mul_f32 v[40:41], v[80:81], v[146:147] op_sel_hi:[1,0]
	s_mov_b32 s12, 0xc000
	v_add_co_u32_e32 v60, vcc, s12, v168
	s_waitcnt lgkmcnt(1)
	v_mfma_f32_16x16x32_bf16 v[8:11], v[48:51], v[8:11], v[40:43]
	v_addc_co_u32_e32 v61, vcc, 0, v169, vcc
	s_mov_b32 s12, 0x4806000
	s_waitcnt lgkmcnt(0)
	v_mfma_f32_16x16x32_bf16 v[68:71], v[52:55], v[12:15], v[8:11]
	v_add_co_u32_e32 v12, vcc, s12, v166
	s_mov_b32 s12, 0x280c000
	s_nop 0
	v_addc_co_u32_e32 v13, vcc, 0, v167, vcc
	v_add_co_u32_e32 v14, vcc, s12, v162
	s_nop 2
	v_cvt_pk_bf16_f32 v8, v68, s0
	v_addc_co_u32_e32 v15, vcc, 0, v163, vcc
	s_mov_b32 s12, 0x1880c000
	v_cvt_pk_bf16_f32 v9, v69, s0
	v_cvt_pk_bf16_f32 v10, v70, s0
	v_cvt_pk_bf16_f32 v11, v71, s0
	ds_write_b16 v180, v8
	ds_write_b16 v180, v9 offset:272
	ds_write_b16 v180, v10 offset:544
	ds_write_b16 v180, v11 offset:816
	v_add_co_u32_e32 v62, vcc, s12, v164
	s_waitcnt lgkmcnt(0)
	s_barrier
	global_load_dwordx4 v[48:51], v[60:61], off offset:64
	global_load_dwordx4 v[52:55], v[60:61], off offset:128
	v_addc_co_u32_e32 v63, vcc, 0, v165, vcc
	global_load_dwordx4 v[56:59], v[60:61], off offset:192
	s_mov_b64 exec, s[0:1]
	global_load_dwordx4 v[40:43], v[12:13], off
	s_mov_b64 exec, -1
	global_load_dwordx4 v[8:11], v[14:15], off
	s_mov_b64 exec, s[0:1]
	global_load_dwordx4 v[44:47], v[12:13], off offset:1024
	s_mov_b64 exec, -1
	s_nop 0
	global_load_dwordx4 v[12:15], v[14:15], off offset:1024
	s_nop 0
	s_mov_b64 exec, s[100:101]
	global_load_ushort v125, v[62:63], off
	global_load_ushort v159, v[62:63], off offset:16
	global_load_ushort v126, v[62:63], off offset:32
	global_load_ushort v127, v[62:63], off offset:48
	s_mov_b64 exec, -1
	s_nop 0
	global_load_dwordx4 v[60:63], v[60:61], off
	s_nop 0
	global_load_dword v124, v239, s[10:11] offset:12
	ds_read_b128 v[80:83], v181
	ds_read_b128 v[108:111], v181 offset:64
	ds_read_b128 v[112:115], v181 offset:128
	ds_read_b128 v[116:119], v181 offset:192
	s_and_b64 vcc, exec, s[6:7]
	s_mov_b64 s[12:13], -1
	s_cbranch_vccnz .LBB0_858
	s_waitcnt lgkmcnt(3)
	v_mfma_f32_16x16x32_bf16 v[120:123], v[80:83], v[24:27], 0
	s_mov_b64 s[12:13], 0
	s_waitcnt lgkmcnt(2)
	v_mfma_f32_16x16x32_bf16 v[120:123], v[108:111], v[28:31], v[120:123]
	s_waitcnt lgkmcnt(1)
	v_mfma_f32_16x16x32_bf16 v[120:123], v[112:115], v[32:35], v[120:123]
	s_waitcnt lgkmcnt(0)
	v_mfma_f32_16x16x32_bf16 v[120:123], v[116:119], v[36:39], v[120:123]

.LBB0_862:
	v_pk_mul_f32 v[16:17], v[146:147], v[68:69] op_sel:[1,0]
	v_pk_mul_f32 v[18:19], v[146:147], v[70:71] op_sel:[1,0]
	s_mov_b32 s12, 0x10000
	s_waitcnt lgkmcnt(1)
	v_mfma_f32_16x16x32_bf16 v[0:3], v[24:27], v[0:3], v[16:19]
	s_waitcnt lgkmcnt(0)
	v_mfma_f32_16x16x32_bf16 v[80:83], v[28:31], v[4:7], v[0:3]
	s_nop 7
	v_cvt_pk_bf16_f32 v0, v80, s0
	v_cvt_pk_bf16_f32 v1, v81, s0
	v_cvt_pk_bf16_f32 v2, v82, s0
	v_cvt_pk_bf16_f32 v3, v83, s0
	ds_write_b16 v180, v0
	ds_write_b16 v180, v1 offset:272
	ds_write_b16 v180, v2 offset:544
	ds_write_b16 v180, v3 offset:816
	v_add_co_u32_e32 v0, vcc, s12, v168
	s_waitcnt lgkmcnt(0)
	s_barrier
	s_mov_b32 s12, 0x4808000
	s_nop 0
	v_addc_co_u32_e32 v1, vcc, 0, v169, vcc
	global_load_dwordx4 v[24:27], v[0:1], off
	global_load_dwordx4 v[28:31], v[0:1], off offset:64
	global_load_dwordx4 v[32:35], v[0:1], off offset:128
	global_load_dwordx4 v[36:39], v[0:1], off offset:192
	v_add_co_u32_e32 v0, vcc, s12, v166
	s_mov_b32 s12, 0x2810000
	s_nop 0
	v_addc_co_u32_e32 v1, vcc, 0, v167, vcc
	v_add_co_u32_e32 v4, vcc, s12, v162
	s_nop 1
	v_addc_co_u32_e32 v5, vcc, 0, v163, vcc
	v_add_co_u32_e32 v64, vcc, 0x18810000, v164
	s_mov_b64 exec, s[0:1]
	global_load_dwordx4 v[20:23], v[0:1], off
	s_mov_b64 exec, -1
	s_mov_b64 exec, s[0:1]
	global_load_dwordx4 v[16:19], v[0:1], off offset:1024
	s_mov_b64 exec, -1
	s_nop 0
	global_load_dwordx4 v[0:3], v[4:5], off
	s_nop 0
	global_load_dwordx4 v[4:7], v[4:5], off offset:1024
	v_addc_co_u32_e32 v65, vcc, 0, v165, vcc
	s_mov_b64 exec, s[100:101]
	global_load_ushort v122, v[64:65], off
	global_load_ushort v123, v[64:65], off offset:16
	global_load_ushort v120, v[64:65], off offset:32
	global_load_ushort v121, v[64:65], off offset:48
	s_mov_b64 exec, -1
	global_load_dword v147, v239, s[10:11] offset:16
	ds_read_b128 v[64:67], v181
	ds_read_b128 v[68:71], v181 offset:64
	ds_read_b128 v[108:111], v181 offset:128
	ds_read_b128 v[112:115], v181 offset:192
	s_and_b64 vcc, exec, s[6:7]
	s_mov_b64 s[10:11], -1
	s_cbranch_vccnz .LBB0_864
	s_waitcnt vmcnt(38) lgkmcnt(3)
	v_mfma_f32_16x16x32_bf16 v[116:119], v[64:67], v[92:95], 0
	s_mov_b64 s[10:11], 0
	s_waitcnt vmcnt(37) lgkmcnt(2)
	v_mfma_f32_16x16x32_bf16 v[116:119], v[68:71], v[96:99], v[116:119]
	s_waitcnt vmcnt(36) lgkmcnt(1)
	v_mfma_f32_16x16x32_bf16 v[116:119], v[108:111], v[100:103], v[116:119]
	s_waitcnt vmcnt(35) lgkmcnt(0)
	v_mfma_f32_16x16x32_bf16 v[116:119], v[112:115], v[104:107], v[116:119]
